# scores epilogue P stores widened to dwordx4 with permlane32_swap plus permlane16_swap (16 contiguous bytes per lane)
# speedup vs baseline: 1.0807x; 1.0044x over previous
; __device__ __forceinline__ u32x2 pk4(f32x4 v) { u32x2 r; r.x = pk_bf16(v[0], v[1]); r.y = pk_bf16(v[2], v[3]); return r; }
; __device__ __forceinline__ f32x4 unpk4(u32x2 v) { return (f32x4){bf_lo(v.x), bf_hi(v.x), bf_lo(v.y), bf_hi(v.y)}; }
;     __device__ __forceinline__ void operator()(const f32x4 (&acc)[2][2][4][2], const Unit& u, int wr, int wc, int fr, int fq) const {
; #pragma unroll
;         for (int ai = 0; ai < 2; ++ai)
; #pragma unroll
;             for (int m = 0; m < 4; ++m) {
;                 const int row = u.pm * 256 + ai * 128 + wr * 64 + m * 16 + fr; float rs = 0.f;
; #pragma unroll
;                 for (int bj = 0; bj < 2; ++bj)
; #pragma unroll
;                     for (int n = 0; n < 2; ++n) {
;                         const f32x4 s = acc[ai][bj][m][n]; f32x4 e;
; #pragma unroll
;                         for (int j = 0; j < 4; ++j) e[j] = __builtin_amdgcn_exp2f(1.44269504089f * s[j]);
;                         const u32x2 w = pk4(e); const f32x4 er = unpk4(w); rs += (er[0] + er[1]) + (er[2] + er[3]);
;                         *(u32x2*)(Q + (size_t)row * 1024 + u.pn * 256 + bj * 128 + wc * 32 + n * 16 + fq * 4) = w;
;                     }
;                 rs += __shfl_xor(rs, 16); rs += __shfl_xor(rs, 32);
;                 if (fq == 0) unsafeAtomicAdd(RSUM + row * 4 + u.pn, rs);
.LBB0_365:
	v_lshrrev_b32_e32 v250, 1, v147
	v_and_b32_e32 v250, 24, v250
	v_mov_b32_e32 v251, 0
	v_and_b32_e32 v135, 64, v147
	v_mul_f32_e32 v124, 0x3fb8aa3b, v124
	v_xor_b32_e32 v134, 16, v147
	v_add_u32_e32 v135, 64, v135
	v_exp_f32_e32 v138, v124
	v_mul_f32_e32 v124, 0x3fb8aa3b, v125
	v_cmp_lt_i32_e32 vcc, v134, v135
	v_exp_f32_e32 v139, v124
	v_mul_f32_e32 v124, 0x3fb8aa3b, v126
	v_cndmask_b32_e32 v134, v147, v134, vcc
	v_exp_f32_e32 v152, v124
	v_mul_f32_e32 v124, 0x3fb8aa3b, v127
	v_lshlrev_b32_e32 v151, 2, v134
	v_xor_b32_e32 v134, 32, v147
	v_exp_f32_e32 v127, v124
	v_cmp_lt_i32_e32 vcc, v134, v135
	s_lshl_b32 s67, s28, 8
	v_cvt_pk_bf16_f32 v126, v138, v139
	v_cndmask_b32_e32 v134, v147, v134, vcc
	v_lshlrev_b32_e32 v150, 2, v134
	v_add_u32_e32 v134, s67, v136
	v_ashrrev_i32_e32 v135, 31, v134
	v_cvt_pk_bf16_f32 v127, v152, v127
	v_lshlrev_b64 v[124:125], 11, v[134:135]
	v_lshlrev_b32_e32 v135, 16, v126
	v_and_b32_e32 v138, 0xffff0000, v126
	v_lshlrev_b32_e32 v139, 16, v127
	v_and_b32_e32 v152, 0xffff0000, v127
	v_add_f32_e32 v135, v135, v138
	v_add_f32_e32 v138, v139, v152
	v_mul_f32_e32 v120, 0x3fb8aa3b, v120
	v_add_f32_e32 v135, v135, v138
	v_exp_f32_e32 v138, v120
	v_mul_f32_e32 v120, 0x3fb8aa3b, v121
	v_exp_f32_e32 v139, v120
	v_mul_f32_e32 v120, 0x3fb8aa3b, v122
	v_exp_f32_e32 v152, v120
	v_mul_f32_e32 v120, 0x3fb8aa3b, v123
	v_exp_f32_e32 v123, v120
	v_mul_f32_e32 v116, 0x3fb8aa3b, v116
	v_mul_f32_e32 v117, 0x3fb8aa3b, v117
	v_mul_f32_e32 v118, 0x3fb8aa3b, v118
	v_mul_f32_e32 v119, 0x3fb8aa3b, v119
	v_exp_f32_e32 v116, v116
	v_exp_f32_e32 v117, v117
	v_exp_f32_e32 v118, v118
	v_exp_f32_e32 v119, v119
	v_cvt_pk_bf16_f32 v122, v138, v139
	v_cvt_pk_bf16_f32 v123, v152, v123
	v_lshl_add_u64 v[120:121], s[46:47], 0, v[124:125]
	v_lshlrev_b32_e32 v124, 16, v122
	v_and_b32_e32 v125, 0xffff0000, v122
	v_lshlrev_b32_e32 v138, 16, v123
	v_and_b32_e32 v139, 0xffff0000, v123
	v_add_f32_e32 v124, v124, v125
	v_add_f32_e32 v125, v138, v139
	v_add_f32_e32 v135, 0, v135
	v_add_f32_e32 v124, v124, v125
	v_cvt_pk_bf16_f32 v116, v116, v117
	v_cvt_pk_bf16_f32 v117, v118, v119
	v_add_f32_e32 v124, v135, v124
	v_lshlrev_b32_e32 v118, 16, v116
	v_and_b32_e32 v119, 0xffff0000, v116
	v_lshlrev_b32_e32 v125, 16, v117
	v_and_b32_e32 v135, 0xffff0000, v117
	v_mul_f32_e32 v114, 0x3fb8aa3b, v114
	v_add_f32_e32 v118, v118, v119
	v_add_f32_e32 v119, v125, v135
	v_mul_f32_e32 v112, 0x3fb8aa3b, v112
	v_mul_f32_e32 v113, 0x3fb8aa3b, v113
	v_exp_f32_e32 v125, v114
	v_mul_f32_e32 v114, 0x3fb8aa3b, v115
	v_exp_f32_e32 v112, v112
	v_exp_f32_e32 v113, v113
	v_exp_f32_e32 v115, v114
	v_add_f32_e32 v114, v118, v119
	v_add_f32_e32 v118, v124, v114
	v_cvt_pk_bf16_f32 v114, v112, v113
	v_cvt_pk_bf16_f32 v115, v125, v115
	v_lshlrev_b32_e32 v112, 16, v114
	v_and_b32_e32 v113, 0xffff0000, v114
	v_lshlrev_b32_e32 v119, 16, v115
	v_and_b32_e32 v124, 0xffff0000, v115
	v_add_f32_e32 v112, v112, v113
	v_add_f32_e32 v113, v119, v124
	v_add_f32_e32 v112, v112, v113
	v_add_f32_e32 v124, v118, v112
	ds_bpermute_b32 v125, v151, v124
	s_lshl_b32 s74, s30, 8
	s_ashr_i32 s75, s74, 31
	v_lshl_add_u64 v[112:113], s[74:75], 1, v[120:121]
	v_lshl_add_u64 v[112:113], v[112:113], 0, s[54:55]
	v_lshl_add_u64 v[118:119], v[112:113], 0, v[132:133]
	s_waitcnt lgkmcnt(0)
	v_add_f32_e32 v112, v124, v125
	ds_bpermute_b32 v113, v150, v112
	v_mov_b32_e32 v200, v126
	v_mov_b32_e32 v201, v127
	v_mov_b32_e32 v202, v122
	v_mov_b32_e32 v203, v123
	v_mov_b32_e32 v204, v116
	v_mov_b32_e32 v205, v117
	v_mov_b32_e32 v206, v114
	v_mov_b32_e32 v207, v115
	v_permlane32_swap_b32_e32 v200, v202
	v_permlane32_swap_b32_e32 v201, v203
	v_permlane32_swap_b32_e32 v204, v206
	v_permlane32_swap_b32_e32 v205, v207
	v_permlane16_swap_b32_e32 v200, v202
	v_permlane16_swap_b32_e32 v201, v203
	v_permlane16_swap_b32_e32 v204, v206
	v_permlane16_swap_b32_e32 v205, v207
	v_lshl_add_u64 v[208:209], v[118:119], 0, v[250:251]
	global_store_dwordx4 v[208:209], v[200:203], off
	global_store_dwordx4 v[208:209], v[204:207], off offset:256
	s_and_saveexec_b64 s[28:29], s[6:7]
	s_cbranch_execz .LBB0_367
	s_waitcnt lgkmcnt(0)
	v_add_f32_e32 v114, v112, v113
	v_lshlrev_b32_e32 v112, 2, v134
	v_ashrrev_i32_e32 v113, 31, v112
	v_lshl_add_u64 v[112:113], v[112:113], 2, s[44:45]
	s_ashr_i32 s31, s30, 31
	v_lshl_add_u64 v[112:113], s[30:31], 2, v[112:113]
	global_atomic_add_f32 v[112:113], v114, off
; __device__ __forceinline__ u32x2 pk4(f32x4 v) { u32x2 r; r.x = pk_bf16(v[0], v[1]); r.y = pk_bf16(v[2], v[3]); return r; }
; __device__ __forceinline__ f32x4 unpk4(u32x2 v) { return (f32x4){bf_lo(v.x), bf_hi(v.x), bf_lo(v.y), bf_hi(v.y)}; }
;     __device__ __forceinline__ void operator()(const f32x4 (&acc)[2][2][4][2], const Unit& u, int wr, int wc, int fr, int fq) const {
; #pragma unroll
;         for (int ai = 0; ai < 2; ++ai)
; #pragma unroll
;             for (int m = 0; m < 4; ++m) {
;                 const int row = u.pm * 256 + ai * 128 + wr * 64 + m * 16 + fr; float rs = 0.f;
; #pragma unroll
;                 for (int bj = 0; bj < 2; ++bj)
; #pragma unroll
;                     for (int n = 0; n < 2; ++n) {
;                         const f32x4 s = acc[ai][bj][m][n]; f32x4 e;
; #pragma unroll
;                         for (int j = 0; j < 4; ++j) e[j] = __builtin_amdgcn_exp2f(1.44269504089f * s[j]);
;                         const u32x2 w = pk4(e); const f32x4 er = unpk4(w); rs += (er[0] + er[1]) + (er[2] + er[3]);
;                         *(u32x2*)(Q + (size_t)row * 1024 + u.pn * 256 + bj * 128 + wc * 32 + n * 16 + fq * 4) = w;
;                     }
;                 rs += __shfl_xor(rs, 16); rs += __shfl_xor(rs, 32);
;                 if (fq == 0) unsafeAtomicAdd(RSUM + row * 4 + u.pn, rs);
.LBB0_367:
	s_or_b64 exec, exec, s[28:29]
	v_mul_f32_e32 v108, 0x3fb8aa3b, v108
	v_exp_f32_e32 v114, v108
	v_mul_f32_e32 v108, 0x3fb8aa3b, v109
	v_exp_f32_e32 v115, v108
	v_mul_f32_e32 v108, 0x3fb8aa3b, v110
	v_exp_f32_e32 v116, v108
	v_mul_f32_e32 v108, 0x3fb8aa3b, v111
	v_exp_f32_e32 v111, v108
	v_mul_f32_e32 v104, 0x3fb8aa3b, v104
	v_mul_f32_e32 v105, 0x3fb8aa3b, v105
	v_mul_f32_e32 v106, 0x3fb8aa3b, v106
	v_mul_f32_e32 v107, 0x3fb8aa3b, v107
	v_or_b32_e32 v112, 16, v136
	v_exp_f32_e32 v104, v104
	v_exp_f32_e32 v105, v105
	v_exp_f32_e32 v106, v106
	v_exp_f32_e32 v107, v107
	v_add_u32_e32 v112, s67, v112
	s_waitcnt lgkmcnt(0)
	v_ashrrev_i32_e32 v113, 31, v112
	v_cvt_pk_bf16_f32 v110, v114, v115
	v_cvt_pk_bf16_f32 v111, v116, v111
	v_mul_f32_e32 v100, 0x3fb8aa3b, v100
	v_mul_f32_e32 v101, 0x3fb8aa3b, v101
	v_mul_f32_e32 v102, 0x3fb8aa3b, v102
	v_mul_f32_e32 v103, 0x3fb8aa3b, v103
	v_lshlrev_b64 v[108:109], 11, v[112:113]
	v_lshlrev_b32_e32 v113, 16, v110
	v_and_b32_e32 v114, 0xffff0000, v110
	v_lshlrev_b32_e32 v115, 16, v111
	v_and_b32_e32 v116, 0xffff0000, v111
	v_exp_f32_e32 v100, v100
	v_exp_f32_e32 v101, v101
	v_exp_f32_e32 v102, v102
	v_exp_f32_e32 v103, v103
	v_add_f32_e32 v113, v113, v114
	v_add_f32_e32 v114, v115, v116
	v_cvt_pk_bf16_f32 v104, v104, v105
	v_cvt_pk_bf16_f32 v105, v106, v107
	v_add_f32_e32 v113, v113, v114
	v_lshlrev_b32_e32 v106, 16, v104
	v_and_b32_e32 v107, 0xffff0000, v104
	v_lshlrev_b32_e32 v114, 16, v105
	v_and_b32_e32 v115, 0xffff0000, v105
	v_add_f32_e32 v106, v106, v107
	v_add_f32_e32 v107, v114, v115
	v_add_f32_e32 v113, 0, v113
	v_add_f32_e32 v106, v106, v107
	v_cvt_pk_bf16_f32 v100, v100, v101
	v_cvt_pk_bf16_f32 v101, v102, v103
	v_add_f32_e32 v106, v113, v106
	v_lshlrev_b32_e32 v102, 16, v100
	v_and_b32_e32 v103, 0xffff0000, v100
	v_lshlrev_b32_e32 v107, 16, v101
	v_and_b32_e32 v113, 0xffff0000, v101
	v_mul_f32_e32 v98, 0x3fb8aa3b, v98
	v_add_f32_e32 v102, v102, v103
	v_add_f32_e32 v103, v107, v113
	v_mul_f32_e32 v96, 0x3fb8aa3b, v96
	v_mul_f32_e32 v97, 0x3fb8aa3b, v97
	v_exp_f32_e32 v107, v98
	v_mul_f32_e32 v98, 0x3fb8aa3b, v99
	v_exp_f32_e32 v96, v96
	v_exp_f32_e32 v97, v97
	v_exp_f32_e32 v99, v98
	v_add_f32_e32 v98, v102, v103
	v_add_f32_e32 v102, v106, v98
	v_cvt_pk_bf16_f32 v98, v96, v97
	v_cvt_pk_bf16_f32 v99, v107, v99
	v_lshlrev_b32_e32 v96, 16, v98
	v_and_b32_e32 v97, 0xffff0000, v98
	v_lshlrev_b32_e32 v103, 16, v99
	v_and_b32_e32 v106, 0xffff0000, v99
	v_add_f32_e32 v96, v96, v97
	v_add_f32_e32 v97, v103, v106
	v_add_f32_e32 v96, v96, v97
	v_add_f32_e32 v106, v102, v96
	ds_bpermute_b32 v107, v151, v106
	v_lshl_add_u64 v[96:97], s[46:47], 0, v[108:109]
	v_lshl_add_u64 v[96:97], s[74:75], 1, v[96:97]
	v_lshl_add_u64 v[96:97], v[96:97], 0, s[54:55]
	v_lshl_add_u64 v[102:103], v[96:97], 0, v[132:133]
	s_waitcnt lgkmcnt(0)
	v_add_f32_e32 v96, v106, v107
	ds_bpermute_b32 v97, v150, v96
	v_mov_b32_e32 v212, v110
	v_mov_b32_e32 v213, v111
	v_mov_b32_e32 v214, v104
	v_mov_b32_e32 v215, v105
	v_mov_b32_e32 v216, v100
	v_mov_b32_e32 v217, v101
	v_mov_b32_e32 v218, v98
	v_mov_b32_e32 v219, v99
	v_permlane32_swap_b32_e32 v212, v214
	v_permlane32_swap_b32_e32 v213, v215
	v_permlane32_swap_b32_e32 v216, v218
	v_permlane32_swap_b32_e32 v217, v219
	v_permlane16_swap_b32_e32 v212, v214
	v_permlane16_swap_b32_e32 v213, v215
	v_permlane16_swap_b32_e32 v216, v218
	v_permlane16_swap_b32_e32 v217, v219
	v_lshl_add_u64 v[208:209], v[102:103], 0, v[250:251]
	global_store_dwordx4 v[208:209], v[212:215], off
	global_store_dwordx4 v[208:209], v[216:219], off offset:256
	s_and_saveexec_b64 s[28:29], s[6:7]
	s_cbranch_execz .LBB0_369
	s_waitcnt lgkmcnt(0)
	v_add_f32_e32 v98, v96, v97
	v_lshlrev_b32_e32 v96, 2, v112
	v_ashrrev_i32_e32 v97, 31, v96
	v_lshl_add_u64 v[96:97], v[96:97], 2, s[44:45]
	s_ashr_i32 s31, s30, 31
	v_lshl_add_u64 v[96:97], s[30:31], 2, v[96:97]
	global_atomic_add_f32 v[96:97], v98, off
.LBB0_369:
	s_or_b64 exec, exec, s[28:29]
	v_mul_f32_e32 v92, 0x3fb8aa3b, v92
	v_exp_f32_e32 v98, v92
	v_mul_f32_e32 v92, 0x3fb8aa3b, v93
	v_exp_f32_e32 v99, v92
	v_mul_f32_e32 v92, 0x3fb8aa3b, v94
	v_exp_f32_e32 v100, v92
	v_mul_f32_e32 v92, 0x3fb8aa3b, v95
	v_exp_f32_e32 v95, v92
	v_mul_f32_e32 v88, 0x3fb8aa3b, v88
	v_mul_f32_e32 v89, 0x3fb8aa3b, v89
	v_mul_f32_e32 v90, 0x3fb8aa3b, v90
	v_mul_f32_e32 v91, 0x3fb8aa3b, v91
	v_exp_f32_e32 v88, v88
	v_exp_f32_e32 v89, v89
	v_exp_f32_e32 v90, v90
	v_exp_f32_e32 v91, v91
	v_add_u32_e32 v96, s67, v254
	s_waitcnt lgkmcnt(0)
	v_ashrrev_i32_e32 v97, 31, v96
	v_cvt_pk_bf16_f32 v94, v98, v99
	v_cvt_pk_bf16_f32 v95, v100, v95
	v_mul_f32_e32 v84, 0x3fb8aa3b, v84
	v_mul_f32_e32 v85, 0x3fb8aa3b, v85
	v_mul_f32_e32 v86, 0x3fb8aa3b, v86
	v_mul_f32_e32 v87, 0x3fb8aa3b, v87
	v_lshlrev_b64 v[92:93], 11, v[96:97]
	v_lshlrev_b32_e32 v97, 16, v94
	v_and_b32_e32 v98, 0xffff0000, v94
	v_lshlrev_b32_e32 v99, 16, v95
	v_and_b32_e32 v100, 0xffff0000, v95
	v_exp_f32_e32 v84, v84
	v_exp_f32_e32 v85, v85
	v_exp_f32_e32 v86, v86
	v_exp_f32_e32 v87, v87
	v_add_f32_e32 v97, v97, v98
	v_add_f32_e32 v98, v99, v100
	v_cvt_pk_bf16_f32 v88, v88, v89
	v_cvt_pk_bf16_f32 v89, v90, v91
	v_add_f32_e32 v97, v97, v98
	v_lshlrev_b32_e32 v90, 16, v88
	v_and_b32_e32 v91, 0xffff0000, v88
	v_lshlrev_b32_e32 v98, 16, v89
	v_and_b32_e32 v99, 0xffff0000, v89
	v_add_f32_e32 v90, v90, v91
	v_add_f32_e32 v91, v98, v99
	v_add_f32_e32 v97, 0, v97
	v_add_f32_e32 v90, v90, v91
	v_cvt_pk_bf16_f32 v84, v84, v85
	v_cvt_pk_bf16_f32 v85, v86, v87
	v_add_f32_e32 v90, v97, v90
	v_lshlrev_b32_e32 v86, 16, v84
	v_and_b32_e32 v87, 0xffff0000, v84
	v_lshlrev_b32_e32 v91, 16, v85
	v_and_b32_e32 v97, 0xffff0000, v85
	v_mul_f32_e32 v82, 0x3fb8aa3b, v82
	v_add_f32_e32 v86, v86, v87
	v_add_f32_e32 v87, v91, v97
	v_mul_f32_e32 v80, 0x3fb8aa3b, v80
	v_mul_f32_e32 v81, 0x3fb8aa3b, v81
	v_exp_f32_e32 v91, v82
	v_mul_f32_e32 v82, 0x3fb8aa3b, v83
	v_exp_f32_e32 v80, v80
	v_exp_f32_e32 v81, v81
	v_exp_f32_e32 v83, v82
	v_add_f32_e32 v82, v86, v87
	v_add_f32_e32 v86, v90, v82
	v_cvt_pk_bf16_f32 v82, v80, v81
	v_cvt_pk_bf16_f32 v83, v91, v83
	v_lshlrev_b32_e32 v80, 16, v82
	v_and_b32_e32 v81, 0xffff0000, v82
	v_lshlrev_b32_e32 v87, 16, v83
	v_and_b32_e32 v90, 0xffff0000, v83
	v_add_f32_e32 v80, v80, v81
	v_add_f32_e32 v81, v87, v90
	v_add_f32_e32 v80, v80, v81
	v_add_f32_e32 v90, v86, v80
	ds_bpermute_b32 v91, v151, v90
	v_lshl_add_u64 v[80:81], s[46:47], 0, v[92:93]
	v_lshl_add_u64 v[80:81], s[74:75], 1, v[80:81]
	v_lshl_add_u64 v[80:81], v[80:81], 0, s[54:55]
	v_lshl_add_u64 v[86:87], v[80:81], 0, v[132:133]
	s_waitcnt lgkmcnt(0)
; __device__ __forceinline__ u32x2 pk4(f32x4 v) { u32x2 r; r.x = pk_bf16(v[0], v[1]); r.y = pk_bf16(v[2], v[3]); return r; }
; __device__ __forceinline__ f32x4 unpk4(u32x2 v) { return (f32x4){bf_lo(v.x), bf_hi(v.x), bf_lo(v.y), bf_hi(v.y)}; }
;     __device__ __forceinline__ void operator()(const f32x4 (&acc)[2][2][4][2], const Unit& u, int wr, int wc, int fr, int fq) const {
; #pragma unroll
;         for (int ai = 0; ai < 2; ++ai)
; #pragma unroll
;             for (int m = 0; m < 4; ++m) {
;                 const int row = u.pm * 256 + ai * 128 + wr * 64 + m * 16 + fr; float rs = 0.f;
; #pragma unroll
;                 for (int bj = 0; bj < 2; ++bj)
; #pragma unroll
;                     for (int n = 0; n < 2; ++n) {
;                         const f32x4 s = acc[ai][bj][m][n]; f32x4 e;
; #pragma unroll
;                         for (int j = 0; j < 4; ++j) e[j] = __builtin_amdgcn_exp2f(1.44269504089f * s[j]);
;                         const u32x2 w = pk4(e); const f32x4 er = unpk4(w); rs += (er[0] + er[1]) + (er[2] + er[3]);
;                         *(u32x2*)(Q + (size_t)row * 1024 + u.pn * 256 + bj * 128 + wc * 32 + n * 16 + fq * 4) = w;
;                     }
;                 rs += __shfl_xor(rs, 16); rs += __shfl_xor(rs, 32);
;                 if (fq == 0) unsafeAtomicAdd(RSUM + row * 4 + u.pn, rs);
	v_add_f32_e32 v80, v90, v91
	ds_bpermute_b32 v81, v150, v80
	v_mov_b32_e32 v200, v94
	v_mov_b32_e32 v201, v95
	v_mov_b32_e32 v202, v88
	v_mov_b32_e32 v203, v89
	v_mov_b32_e32 v204, v84
	v_mov_b32_e32 v205, v85
	v_mov_b32_e32 v206, v82
	v_mov_b32_e32 v207, v83
	v_permlane32_swap_b32_e32 v200, v202
	v_permlane32_swap_b32_e32 v201, v203
	v_permlane32_swap_b32_e32 v204, v206
	v_permlane32_swap_b32_e32 v205, v207
	v_permlane16_swap_b32_e32 v200, v202
	v_permlane16_swap_b32_e32 v201, v203
	v_permlane16_swap_b32_e32 v204, v206
	v_permlane16_swap_b32_e32 v205, v207
	v_lshl_add_u64 v[208:209], v[86:87], 0, v[250:251]
	global_store_dwordx4 v[208:209], v[200:203], off
	global_store_dwordx4 v[208:209], v[204:207], off offset:256
	s_and_saveexec_b64 s[28:29], s[6:7]
	s_cbranch_execz .LBB0_371
	s_waitcnt lgkmcnt(0)
	v_add_f32_e32 v82, v80, v81
	v_lshlrev_b32_e32 v80, 2, v96
	v_ashrrev_i32_e32 v81, 31, v80
	v_lshl_add_u64 v[80:81], v[80:81], 2, s[44:45]
	s_ashr_i32 s31, s30, 31
	v_lshl_add_u64 v[80:81], s[30:31], 2, v[80:81]
	global_atomic_add_f32 v[80:81], v82, off
.LBB0_371:
	s_or_b64 exec, exec, s[28:29]
	v_mul_f32_e32 v76, 0x3fb8aa3b, v76
	v_exp_f32_e32 v82, v76
	v_mul_f32_e32 v76, 0x3fb8aa3b, v77
	v_exp_f32_e32 v83, v76
	v_mul_f32_e32 v76, 0x3fb8aa3b, v78
	v_exp_f32_e32 v84, v76
	v_mul_f32_e32 v76, 0x3fb8aa3b, v79
	v_exp_f32_e32 v79, v76
	v_mul_f32_e32 v72, 0x3fb8aa3b, v72
	v_mul_f32_e32 v73, 0x3fb8aa3b, v73
	v_mul_f32_e32 v74, 0x3fb8aa3b, v74
	v_mul_f32_e32 v75, 0x3fb8aa3b, v75
	v_exp_f32_e32 v72, v72
	v_exp_f32_e32 v73, v73
	v_exp_f32_e32 v74, v74
	v_exp_f32_e32 v75, v75
	v_add_u32_e32 v80, s67, v137
	s_waitcnt lgkmcnt(0)
	v_ashrrev_i32_e32 v81, 31, v80
	v_cvt_pk_bf16_f32 v78, v82, v83
	v_cvt_pk_bf16_f32 v79, v84, v79
	v_mul_f32_e32 v68, 0x3fb8aa3b, v68
	v_mul_f32_e32 v69, 0x3fb8aa3b, v69
	v_mul_f32_e32 v70, 0x3fb8aa3b, v70
	v_mul_f32_e32 v71, 0x3fb8aa3b, v71
	v_lshlrev_b64 v[76:77], 11, v[80:81]
	v_lshlrev_b32_e32 v81, 16, v78
	v_and_b32_e32 v82, 0xffff0000, v78
	v_lshlrev_b32_e32 v83, 16, v79
	v_and_b32_e32 v84, 0xffff0000, v79
	v_exp_f32_e32 v68, v68
	v_exp_f32_e32 v69, v69
	v_exp_f32_e32 v70, v70
	v_exp_f32_e32 v71, v71
	v_add_f32_e32 v81, v81, v82
	v_add_f32_e32 v82, v83, v84
	v_cvt_pk_bf16_f32 v72, v72, v73
	v_cvt_pk_bf16_f32 v73, v74, v75
	v_add_f32_e32 v81, v81, v82
	v_lshlrev_b32_e32 v74, 16, v72
	v_and_b32_e32 v75, 0xffff0000, v72
	v_lshlrev_b32_e32 v82, 16, v73
	v_and_b32_e32 v83, 0xffff0000, v73
	v_add_f32_e32 v74, v74, v75
	v_add_f32_e32 v75, v82, v83
	v_add_f32_e32 v81, 0, v81
	v_add_f32_e32 v74, v74, v75
	v_cvt_pk_bf16_f32 v68, v68, v69
	v_cvt_pk_bf16_f32 v69, v70, v71
	v_add_f32_e32 v74, v81, v74
	v_lshlrev_b32_e32 v70, 16, v68
	v_and_b32_e32 v71, 0xffff0000, v68
	v_lshlrev_b32_e32 v75, 16, v69
	v_and_b32_e32 v81, 0xffff0000, v69
	v_mul_f32_e32 v66, 0x3fb8aa3b, v66
	v_add_f32_e32 v70, v70, v71
	v_add_f32_e32 v71, v75, v81
	v_mul_f32_e32 v64, 0x3fb8aa3b, v64
	v_mul_f32_e32 v65, 0x3fb8aa3b, v65
	v_exp_f32_e32 v75, v66
	v_mul_f32_e32 v66, 0x3fb8aa3b, v67
	v_exp_f32_e32 v64, v64
	v_exp_f32_e32 v65, v65
	v_exp_f32_e32 v67, v66
	v_add_f32_e32 v66, v70, v71
	v_add_f32_e32 v70, v74, v66
	v_cvt_pk_bf16_f32 v66, v64, v65
	v_cvt_pk_bf16_f32 v67, v75, v67
	v_lshlrev_b32_e32 v64, 16, v66
	v_and_b32_e32 v65, 0xffff0000, v66
	v_lshlrev_b32_e32 v71, 16, v67
	v_and_b32_e32 v74, 0xffff0000, v67
	v_add_f32_e32 v64, v64, v65
	v_add_f32_e32 v65, v71, v74
	v_add_f32_e32 v64, v64, v65
	v_add_f32_e32 v74, v70, v64
	ds_bpermute_b32 v75, v151, v74
	v_lshl_add_u64 v[64:65], s[46:47], 0, v[76:77]
	v_lshl_add_u64 v[64:65], s[74:75], 1, v[64:65]
	v_lshl_add_u64 v[64:65], v[64:65], 0, s[54:55]
	v_lshl_add_u64 v[70:71], v[64:65], 0, v[132:133]
	s_waitcnt lgkmcnt(0)
	v_add_f32_e32 v64, v74, v75
	ds_bpermute_b32 v65, v150, v64
	v_mov_b32_e32 v212, v78
	v_mov_b32_e32 v213, v79
	v_mov_b32_e32 v214, v72
	v_mov_b32_e32 v215, v73
	v_mov_b32_e32 v216, v68
	v_mov_b32_e32 v217, v69
	v_mov_b32_e32 v218, v66
	v_mov_b32_e32 v219, v67
	v_permlane32_swap_b32_e32 v212, v214
	v_permlane32_swap_b32_e32 v213, v215
	v_permlane32_swap_b32_e32 v216, v218
	v_permlane32_swap_b32_e32 v217, v219
	v_permlane16_swap_b32_e32 v212, v214
	v_permlane16_swap_b32_e32 v213, v215
	v_permlane16_swap_b32_e32 v216, v218
	v_permlane16_swap_b32_e32 v217, v219
	v_lshl_add_u64 v[208:209], v[70:71], 0, v[250:251]
	global_store_dwordx4 v[208:209], v[212:215], off
	global_store_dwordx4 v[208:209], v[216:219], off offset:256
	s_and_saveexec_b64 s[28:29], s[6:7]
	s_cbranch_execz .LBB0_373
	s_waitcnt lgkmcnt(0)
	v_add_f32_e32 v66, v64, v65
	v_lshlrev_b32_e32 v64, 2, v80
	v_ashrrev_i32_e32 v65, 31, v64
	v_lshl_add_u64 v[64:65], v[64:65], 2, s[44:45]
	s_ashr_i32 s31, s30, 31
	v_lshl_add_u64 v[64:65], s[30:31], 2, v[64:65]
	global_atomic_add_f32 v[64:65], v66, off
; __device__ __forceinline__ u32x2 pk4(f32x4 v) { u32x2 r; r.x = pk_bf16(v[0], v[1]); r.y = pk_bf16(v[2], v[3]); return r; }
; __device__ __forceinline__ f32x4 unpk4(u32x2 v) { return (f32x4){bf_lo(v.x), bf_hi(v.x), bf_lo(v.y), bf_hi(v.y)}; }
;     __device__ __forceinline__ void operator()(const f32x4 (&acc)[2][2][4][2], const Unit& u, int wr, int wc, int fr, int fq) const {
; #pragma unroll
;         for (int ai = 0; ai < 2; ++ai)
; #pragma unroll
;             for (int m = 0; m < 4; ++m) {
;                 const int row = u.pm * 256 + ai * 128 + wr * 64 + m * 16 + fr; float rs = 0.f;
; #pragma unroll
;                 for (int bj = 0; bj < 2; ++bj)
; #pragma unroll
;                     for (int n = 0; n < 2; ++n) {
;                         const f32x4 s = acc[ai][bj][m][n]; f32x4 e;
; #pragma unroll
;                         for (int j = 0; j < 4; ++j) e[j] = __builtin_amdgcn_exp2f(1.44269504089f * s[j]);
;                         const u32x2 w = pk4(e); const f32x4 er = unpk4(w); rs += (er[0] + er[1]) + (er[2] + er[3]);
;                         *(u32x2*)(Q + (size_t)row * 1024 + u.pn * 256 + bj * 128 + wc * 32 + n * 16 + fq * 4) = w;
;                     }
;                 rs += __shfl_xor(rs, 16); rs += __shfl_xor(rs, 32);
;                 if (fq == 0) unsafeAtomicAdd(RSUM + row * 4 + u.pn, rs);
.LBB0_373:
	s_or_b64 exec, exec, s[28:29]
	v_mul_f32_e32 v60, 0x3fb8aa3b, v60
	v_exp_f32_e32 v66, v60
	v_mul_f32_e32 v60, 0x3fb8aa3b, v61
	v_exp_f32_e32 v67, v60
	v_mul_f32_e32 v60, 0x3fb8aa3b, v62
	v_exp_f32_e32 v68, v60
	v_mul_f32_e32 v60, 0x3fb8aa3b, v63
	v_exp_f32_e32 v63, v60
	v_mul_f32_e32 v56, 0x3fb8aa3b, v56
	v_mul_f32_e32 v57, 0x3fb8aa3b, v57
	v_mul_f32_e32 v58, 0x3fb8aa3b, v58
	v_mul_f32_e32 v59, 0x3fb8aa3b, v59
	v_exp_f32_e32 v56, v56
	v_exp_f32_e32 v57, v57
	v_exp_f32_e32 v58, v58
	v_exp_f32_e32 v59, v59
	v_add_u32_e32 v64, s67, v140
	s_waitcnt lgkmcnt(0)
	v_ashrrev_i32_e32 v65, 31, v64
	v_cvt_pk_bf16_f32 v62, v66, v67
	v_cvt_pk_bf16_f32 v63, v68, v63
	v_mul_f32_e32 v52, 0x3fb8aa3b, v52
	v_mul_f32_e32 v53, 0x3fb8aa3b, v53
	v_mul_f32_e32 v54, 0x3fb8aa3b, v54
	v_mul_f32_e32 v55, 0x3fb8aa3b, v55
	v_lshlrev_b64 v[60:61], 11, v[64:65]
	v_lshlrev_b32_e32 v65, 16, v62
	v_and_b32_e32 v66, 0xffff0000, v62
	v_lshlrev_b32_e32 v67, 16, v63
	v_and_b32_e32 v68, 0xffff0000, v63
	v_exp_f32_e32 v52, v52
	v_exp_f32_e32 v53, v53
	v_exp_f32_e32 v54, v54
	v_exp_f32_e32 v55, v55
	v_add_f32_e32 v65, v65, v66
	v_add_f32_e32 v66, v67, v68
	v_cvt_pk_bf16_f32 v56, v56, v57
	v_cvt_pk_bf16_f32 v57, v58, v59
	v_add_f32_e32 v65, v65, v66
	v_lshlrev_b32_e32 v58, 16, v56
	v_and_b32_e32 v59, 0xffff0000, v56
	v_lshlrev_b32_e32 v66, 16, v57
	v_and_b32_e32 v67, 0xffff0000, v57
	v_add_f32_e32 v58, v58, v59
	v_add_f32_e32 v59, v66, v67
	v_add_f32_e32 v65, 0, v65
	v_add_f32_e32 v58, v58, v59
	v_cvt_pk_bf16_f32 v52, v52, v53
	v_cvt_pk_bf16_f32 v53, v54, v55
	v_add_f32_e32 v58, v65, v58
	v_lshlrev_b32_e32 v54, 16, v52
	v_and_b32_e32 v55, 0xffff0000, v52
	v_lshlrev_b32_e32 v59, 16, v53
	v_and_b32_e32 v65, 0xffff0000, v53
	v_mul_f32_e32 v50, 0x3fb8aa3b, v50
	v_add_f32_e32 v54, v54, v55
	v_add_f32_e32 v55, v59, v65
	v_mul_f32_e32 v48, 0x3fb8aa3b, v48
	v_mul_f32_e32 v49, 0x3fb8aa3b, v49
	v_exp_f32_e32 v59, v50
	v_mul_f32_e32 v50, 0x3fb8aa3b, v51
	v_exp_f32_e32 v48, v48
	v_exp_f32_e32 v49, v49
	v_exp_f32_e32 v51, v50
	v_add_f32_e32 v50, v54, v55
	v_add_f32_e32 v54, v58, v50
	v_cvt_pk_bf16_f32 v50, v48, v49
	v_cvt_pk_bf16_f32 v51, v59, v51
	v_lshlrev_b32_e32 v48, 16, v50
	v_and_b32_e32 v49, 0xffff0000, v50
	v_lshlrev_b32_e32 v55, 16, v51
	v_and_b32_e32 v58, 0xffff0000, v51
	v_add_f32_e32 v48, v48, v49
	v_add_f32_e32 v49, v55, v58
	v_add_f32_e32 v48, v48, v49
	v_add_f32_e32 v58, v54, v48
	ds_bpermute_b32 v59, v151, v58
	v_lshl_add_u64 v[48:49], s[46:47], 0, v[60:61]
	v_lshl_add_u64 v[48:49], s[74:75], 1, v[48:49]
	v_lshl_add_u64 v[48:49], v[48:49], 0, s[54:55]
	v_lshl_add_u64 v[54:55], v[48:49], 0, v[132:133]
	s_waitcnt lgkmcnt(0)
	v_add_f32_e32 v48, v58, v59
	ds_bpermute_b32 v49, v150, v48
	v_mov_b32_e32 v200, v62
	v_mov_b32_e32 v201, v63
	v_mov_b32_e32 v202, v56
	v_mov_b32_e32 v203, v57
	v_mov_b32_e32 v204, v52
	v_mov_b32_e32 v205, v53
	v_mov_b32_e32 v206, v50
	v_mov_b32_e32 v207, v51
	v_permlane32_swap_b32_e32 v200, v202
	v_permlane32_swap_b32_e32 v201, v203
	v_permlane32_swap_b32_e32 v204, v206
	v_permlane32_swap_b32_e32 v205, v207
	v_permlane16_swap_b32_e32 v200, v202
	v_permlane16_swap_b32_e32 v201, v203
	v_permlane16_swap_b32_e32 v204, v206
	v_permlane16_swap_b32_e32 v205, v207
	v_lshl_add_u64 v[208:209], v[54:55], 0, v[250:251]
	global_store_dwordx4 v[208:209], v[200:203], off
	global_store_dwordx4 v[208:209], v[204:207], off offset:256
	s_and_saveexec_b64 s[28:29], s[6:7]
	s_cbranch_execz .LBB0_375
	s_waitcnt lgkmcnt(0)
	v_add_f32_e32 v50, v48, v49
	v_lshlrev_b32_e32 v48, 2, v64
	v_ashrrev_i32_e32 v49, 31, v48
	v_lshl_add_u64 v[48:49], v[48:49], 2, s[44:45]
	s_ashr_i32 s31, s30, 31
	v_lshl_add_u64 v[48:49], s[30:31], 2, v[48:49]
	global_atomic_add_f32 v[48:49], v50, off
.LBB0_375:
	s_or_b64 exec, exec, s[28:29]
	v_mul_f32_e32 v44, 0x3fb8aa3b, v44
	v_exp_f32_e32 v50, v44
	v_mul_f32_e32 v44, 0x3fb8aa3b, v45
	v_exp_f32_e32 v51, v44
	v_mul_f32_e32 v44, 0x3fb8aa3b, v46
	v_exp_f32_e32 v52, v44
	v_mul_f32_e32 v44, 0x3fb8aa3b, v47
	v_exp_f32_e32 v47, v44
	v_mul_f32_e32 v40, 0x3fb8aa3b, v40
	v_mul_f32_e32 v41, 0x3fb8aa3b, v41
	v_mul_f32_e32 v42, 0x3fb8aa3b, v42
	v_mul_f32_e32 v43, 0x3fb8aa3b, v43
	v_exp_f32_e32 v40, v40
	v_exp_f32_e32 v41, v41
	v_exp_f32_e32 v42, v42
	v_exp_f32_e32 v43, v43
	v_add_u32_e32 v48, s67, v141
	s_waitcnt lgkmcnt(0)
	v_ashrrev_i32_e32 v49, 31, v48
	v_cvt_pk_bf16_f32 v46, v50, v51
	v_cvt_pk_bf16_f32 v47, v52, v47
	v_mul_f32_e32 v36, 0x3fb8aa3b, v36
	v_mul_f32_e32 v37, 0x3fb8aa3b, v37
	v_mul_f32_e32 v38, 0x3fb8aa3b, v38
	v_mul_f32_e32 v39, 0x3fb8aa3b, v39
	v_lshlrev_b64 v[44:45], 11, v[48:49]
	v_lshlrev_b32_e32 v49, 16, v46
	v_and_b32_e32 v50, 0xffff0000, v46
	v_lshlrev_b32_e32 v51, 16, v47
	v_and_b32_e32 v52, 0xffff0000, v47
	v_exp_f32_e32 v36, v36
	v_exp_f32_e32 v37, v37
	v_exp_f32_e32 v38, v38
	v_exp_f32_e32 v39, v39
	v_add_f32_e32 v49, v49, v50
	v_add_f32_e32 v50, v51, v52
	v_cvt_pk_bf16_f32 v40, v40, v41
	v_cvt_pk_bf16_f32 v41, v42, v43
	v_add_f32_e32 v49, v49, v50
	v_lshlrev_b32_e32 v42, 16, v40
	v_and_b32_e32 v43, 0xffff0000, v40
	v_lshlrev_b32_e32 v50, 16, v41
	v_and_b32_e32 v51, 0xffff0000, v41
	v_add_f32_e32 v42, v42, v43
	v_add_f32_e32 v43, v50, v51
	v_add_f32_e32 v49, 0, v49
	v_add_f32_e32 v42, v42, v43
	v_cvt_pk_bf16_f32 v36, v36, v37
	v_cvt_pk_bf16_f32 v37, v38, v39
	v_add_f32_e32 v42, v49, v42
	v_lshlrev_b32_e32 v38, 16, v36
	v_and_b32_e32 v39, 0xffff0000, v36
	v_lshlrev_b32_e32 v43, 16, v37
	v_and_b32_e32 v49, 0xffff0000, v37
	v_mul_f32_e32 v34, 0x3fb8aa3b, v34
	v_add_f32_e32 v38, v38, v39
	v_add_f32_e32 v39, v43, v49
	v_mul_f32_e32 v32, 0x3fb8aa3b, v32
	v_mul_f32_e32 v33, 0x3fb8aa3b, v33
	v_exp_f32_e32 v43, v34
	v_mul_f32_e32 v34, 0x3fb8aa3b, v35
	v_exp_f32_e32 v32, v32
	v_exp_f32_e32 v33, v33
	v_exp_f32_e32 v35, v34
	v_add_f32_e32 v34, v38, v39
	v_add_f32_e32 v38, v42, v34
	v_cvt_pk_bf16_f32 v34, v32, v33
	v_cvt_pk_bf16_f32 v35, v43, v35
	v_lshlrev_b32_e32 v32, 16, v34
	v_and_b32_e32 v33, 0xffff0000, v34
	v_lshlrev_b32_e32 v39, 16, v35
	v_and_b32_e32 v42, 0xffff0000, v35
	v_add_f32_e32 v32, v32, v33
	v_add_f32_e32 v33, v39, v42
	v_add_f32_e32 v32, v32, v33
	v_add_f32_e32 v42, v38, v32
	ds_bpermute_b32 v43, v151, v42
	v_lshl_add_u64 v[32:33], s[46:47], 0, v[44:45]
	v_lshl_add_u64 v[32:33], s[74:75], 1, v[32:33]
	v_lshl_add_u64 v[32:33], v[32:33], 0, s[54:55]
	v_lshl_add_u64 v[38:39], v[32:33], 0, v[132:133]
	s_waitcnt lgkmcnt(0)
; __device__ __forceinline__ u32x2 pk4(f32x4 v) { u32x2 r; r.x = pk_bf16(v[0], v[1]); r.y = pk_bf16(v[2], v[3]); return r; }
; __device__ __forceinline__ f32x4 unpk4(u32x2 v) { return (f32x4){bf_lo(v.x), bf_hi(v.x), bf_lo(v.y), bf_hi(v.y)}; }
;     __device__ __forceinline__ void operator()(const f32x4 (&acc)[2][2][4][2], const Unit& u, int wr, int wc, int fr, int fq) const {
; #pragma unroll
;         for (int ai = 0; ai < 2; ++ai)
; #pragma unroll
;             for (int m = 0; m < 4; ++m) {
;                 const int row = u.pm * 256 + ai * 128 + wr * 64 + m * 16 + fr; float rs = 0.f;
; #pragma unroll
;                 for (int bj = 0; bj < 2; ++bj)
; #pragma unroll
;                     for (int n = 0; n < 2; ++n) {
;                         const f32x4 s = acc[ai][bj][m][n]; f32x4 e;
; #pragma unroll
;                         for (int j = 0; j < 4; ++j) e[j] = __builtin_amdgcn_exp2f(1.44269504089f * s[j]);
;                         const u32x2 w = pk4(e); const f32x4 er = unpk4(w); rs += (er[0] + er[1]) + (er[2] + er[3]);
;                         *(u32x2*)(Q + (size_t)row * 1024 + u.pn * 256 + bj * 128 + wc * 32 + n * 16 + fq * 4) = w;
;                     }
;                 rs += __shfl_xor(rs, 16); rs += __shfl_xor(rs, 32);
;                 if (fq == 0) unsafeAtomicAdd(RSUM + row * 4 + u.pn, rs);
	v_add_f32_e32 v32, v42, v43
	ds_bpermute_b32 v33, v150, v32
	v_mov_b32_e32 v212, v46
	v_mov_b32_e32 v213, v47
	v_mov_b32_e32 v214, v40
	v_mov_b32_e32 v215, v41
	v_mov_b32_e32 v216, v36
	v_mov_b32_e32 v217, v37
	v_mov_b32_e32 v218, v34
	v_mov_b32_e32 v219, v35
	v_permlane32_swap_b32_e32 v212, v214
	v_permlane32_swap_b32_e32 v213, v215
	v_permlane32_swap_b32_e32 v216, v218
	v_permlane32_swap_b32_e32 v217, v219
	v_permlane16_swap_b32_e32 v212, v214
	v_permlane16_swap_b32_e32 v213, v215
	v_permlane16_swap_b32_e32 v216, v218
	v_permlane16_swap_b32_e32 v217, v219
	v_lshl_add_u64 v[208:209], v[38:39], 0, v[250:251]
	global_store_dwordx4 v[208:209], v[212:215], off
	global_store_dwordx4 v[208:209], v[216:219], off offset:256
	s_and_saveexec_b64 s[28:29], s[6:7]
	s_cbranch_execz .LBB0_377
	s_waitcnt lgkmcnt(0)
	v_add_f32_e32 v34, v32, v33
	v_lshlrev_b32_e32 v32, 2, v48
	v_ashrrev_i32_e32 v33, 31, v32
	v_lshl_add_u64 v[32:33], v[32:33], 2, s[44:45]
	s_ashr_i32 s31, s30, 31
	v_lshl_add_u64 v[32:33], s[30:31], 2, v[32:33]
	global_atomic_add_f32 v[32:33], v34, off
.LBB0_377:
	s_or_b64 exec, exec, s[28:29]
	v_mul_f32_e32 v28, 0x3fb8aa3b, v28
	v_exp_f32_e32 v34, v28
	v_mul_f32_e32 v28, 0x3fb8aa3b, v29
	v_exp_f32_e32 v35, v28
	v_mul_f32_e32 v28, 0x3fb8aa3b, v30
	v_exp_f32_e32 v36, v28
	v_mul_f32_e32 v28, 0x3fb8aa3b, v31
	v_exp_f32_e32 v31, v28
	v_mul_f32_e32 v24, 0x3fb8aa3b, v24
	v_mul_f32_e32 v25, 0x3fb8aa3b, v25
	v_mul_f32_e32 v26, 0x3fb8aa3b, v26
	v_mul_f32_e32 v27, 0x3fb8aa3b, v27
	v_exp_f32_e32 v24, v24
	v_exp_f32_e32 v25, v25
	v_exp_f32_e32 v26, v26
	v_exp_f32_e32 v27, v27
	v_add_u32_e32 v32, s67, v142
	s_waitcnt lgkmcnt(0)
	v_ashrrev_i32_e32 v33, 31, v32
	v_cvt_pk_bf16_f32 v30, v34, v35
	v_cvt_pk_bf16_f32 v31, v36, v31
	v_mul_f32_e32 v20, 0x3fb8aa3b, v20
	v_mul_f32_e32 v21, 0x3fb8aa3b, v21
	v_mul_f32_e32 v22, 0x3fb8aa3b, v22
	v_mul_f32_e32 v23, 0x3fb8aa3b, v23
	v_lshlrev_b64 v[28:29], 11, v[32:33]
	v_lshlrev_b32_e32 v33, 16, v30
	v_and_b32_e32 v34, 0xffff0000, v30
	v_lshlrev_b32_e32 v35, 16, v31
	v_and_b32_e32 v36, 0xffff0000, v31
	v_exp_f32_e32 v20, v20
	v_exp_f32_e32 v21, v21
	v_exp_f32_e32 v22, v22
	v_exp_f32_e32 v23, v23
	v_add_f32_e32 v33, v33, v34
	v_add_f32_e32 v34, v35, v36
	v_cvt_pk_bf16_f32 v24, v24, v25
	v_cvt_pk_bf16_f32 v25, v26, v27
	v_add_f32_e32 v33, v33, v34
	v_lshlrev_b32_e32 v26, 16, v24
	v_and_b32_e32 v27, 0xffff0000, v24
	v_lshlrev_b32_e32 v34, 16, v25
	v_and_b32_e32 v35, 0xffff0000, v25
	v_add_f32_e32 v26, v26, v27
	v_add_f32_e32 v27, v34, v35
	v_add_f32_e32 v33, 0, v33
	v_add_f32_e32 v26, v26, v27
	v_cvt_pk_bf16_f32 v20, v20, v21
	v_cvt_pk_bf16_f32 v21, v22, v23
	v_add_f32_e32 v26, v33, v26
	v_lshlrev_b32_e32 v22, 16, v20
	v_and_b32_e32 v23, 0xffff0000, v20
	v_lshlrev_b32_e32 v27, 16, v21
	v_and_b32_e32 v33, 0xffff0000, v21
	v_mul_f32_e32 v18, 0x3fb8aa3b, v18
	v_add_f32_e32 v22, v22, v23
	v_add_f32_e32 v23, v27, v33
	v_mul_f32_e32 v16, 0x3fb8aa3b, v16
	v_mul_f32_e32 v17, 0x3fb8aa3b, v17
	v_exp_f32_e32 v27, v18
	v_mul_f32_e32 v18, 0x3fb8aa3b, v19
	v_exp_f32_e32 v16, v16
	v_exp_f32_e32 v17, v17
	v_exp_f32_e32 v19, v18
	v_add_f32_e32 v18, v22, v23
	v_add_f32_e32 v22, v26, v18
	v_cvt_pk_bf16_f32 v18, v16, v17
	v_cvt_pk_bf16_f32 v19, v27, v19
	v_lshlrev_b32_e32 v16, 16, v18
	v_and_b32_e32 v17, 0xffff0000, v18
	v_lshlrev_b32_e32 v23, 16, v19
	v_and_b32_e32 v26, 0xffff0000, v19
	v_add_f32_e32 v16, v16, v17
	v_add_f32_e32 v17, v23, v26
	v_add_f32_e32 v16, v16, v17
	v_add_f32_e32 v26, v22, v16
	ds_bpermute_b32 v27, v151, v26
	v_lshl_add_u64 v[16:17], s[46:47], 0, v[28:29]
	v_lshl_add_u64 v[16:17], s[74:75], 1, v[16:17]
	v_lshl_add_u64 v[16:17], v[16:17], 0, s[54:55]
	v_lshl_add_u64 v[22:23], v[16:17], 0, v[132:133]
	s_waitcnt lgkmcnt(0)
	v_add_f32_e32 v16, v26, v27
	ds_bpermute_b32 v17, v150, v16
	v_mov_b32_e32 v200, v30
	v_mov_b32_e32 v201, v31
	v_mov_b32_e32 v202, v24
	v_mov_b32_e32 v203, v25
	v_mov_b32_e32 v204, v20
	v_mov_b32_e32 v205, v21
	v_mov_b32_e32 v206, v18
	v_mov_b32_e32 v207, v19
	v_permlane32_swap_b32_e32 v200, v202
	v_permlane32_swap_b32_e32 v201, v203
	v_permlane32_swap_b32_e32 v204, v206
	v_permlane32_swap_b32_e32 v205, v207
	v_permlane16_swap_b32_e32 v200, v202
	v_permlane16_swap_b32_e32 v201, v203
	v_permlane16_swap_b32_e32 v204, v206
	v_permlane16_swap_b32_e32 v205, v207
	v_lshl_add_u64 v[208:209], v[22:23], 0, v[250:251]
	global_store_dwordx4 v[208:209], v[200:203], off
	global_store_dwordx4 v[208:209], v[204:207], off offset:256
	s_and_saveexec_b64 s[28:29], s[6:7]
	s_cbranch_execz .LBB0_379
	s_waitcnt lgkmcnt(0)
	v_add_f32_e32 v18, v16, v17
	v_lshlrev_b32_e32 v16, 2, v32
	v_ashrrev_i32_e32 v17, 31, v16
	v_lshl_add_u64 v[16:17], v[16:17], 2, s[44:45]
	s_ashr_i32 s31, s30, 31
	v_lshl_add_u64 v[16:17], s[30:31], 2, v[16:17]
	global_atomic_add_f32 v[16:17], v18, off
; __device__ __forceinline__ u32x2 pk4(f32x4 v) { u32x2 r; r.x = pk_bf16(v[0], v[1]); r.y = pk_bf16(v[2], v[3]); return r; }
; __device__ __forceinline__ f32x4 unpk4(u32x2 v) { return (f32x4){bf_lo(v.x), bf_hi(v.x), bf_lo(v.y), bf_hi(v.y)}; }
;     __device__ __forceinline__ void operator()(const f32x4 (&acc)[2][2][4][2], const Unit& u, int wr, int wc, int fr, int fq) const {
; #pragma unroll
;         for (int ai = 0; ai < 2; ++ai)
; #pragma unroll
;             for (int m = 0; m < 4; ++m) {
;                 const int row = u.pm * 256 + ai * 128 + wr * 64 + m * 16 + fr; float rs = 0.f;
; #pragma unroll
;                 for (int bj = 0; bj < 2; ++bj)
; #pragma unroll
;                     for (int n = 0; n < 2; ++n) {
;                         const f32x4 s = acc[ai][bj][m][n]; f32x4 e;
; #pragma unroll
;                         for (int j = 0; j < 4; ++j) e[j] = __builtin_amdgcn_exp2f(1.44269504089f * s[j]);
;                         const u32x2 w = pk4(e); const f32x4 er = unpk4(w); rs += (er[0] + er[1]) + (er[2] + er[3]);
;                         *(u32x2*)(Q + (size_t)row * 1024 + u.pn * 256 + bj * 128 + wc * 32 + n * 16 + fq * 4) = w;
;                     }
;                 rs += __shfl_xor(rs, 16); rs += __shfl_xor(rs, 32);
;                 if (fq == 0) unsafeAtomicAdd(RSUM + row * 4 + u.pn, rs);
.LBB0_379:
	s_or_b64 exec, exec, s[28:29]
	v_mul_f32_e32 v12, 0x3fb8aa3b, v12
	v_exp_f32_e32 v18, v12
	v_mul_f32_e32 v12, 0x3fb8aa3b, v13
	v_exp_f32_e32 v19, v12
	v_mul_f32_e32 v12, 0x3fb8aa3b, v14
	v_exp_f32_e32 v20, v12
	v_mul_f32_e32 v12, 0x3fb8aa3b, v15
	v_exp_f32_e32 v15, v12
	v_mul_f32_e32 v8, 0x3fb8aa3b, v8
	v_mul_f32_e32 v9, 0x3fb8aa3b, v9
	v_mul_f32_e32 v10, 0x3fb8aa3b, v10
	v_mul_f32_e32 v11, 0x3fb8aa3b, v11
	v_exp_f32_e32 v8, v8
	v_exp_f32_e32 v9, v9
	v_exp_f32_e32 v10, v10
	v_exp_f32_e32 v11, v11
	v_add_u32_e32 v16, s67, v143
	s_waitcnt lgkmcnt(0)
	v_ashrrev_i32_e32 v17, 31, v16
	v_cvt_pk_bf16_f32 v14, v18, v19
	v_cvt_pk_bf16_f32 v15, v20, v15
	v_mul_f32_e32 v4, 0x3fb8aa3b, v4
	v_mul_f32_e32 v5, 0x3fb8aa3b, v5
	v_mul_f32_e32 v6, 0x3fb8aa3b, v6
	v_mul_f32_e32 v7, 0x3fb8aa3b, v7
	v_lshlrev_b64 v[12:13], 11, v[16:17]
	v_lshlrev_b32_e32 v17, 16, v14
	v_and_b32_e32 v18, 0xffff0000, v14
	v_lshlrev_b32_e32 v19, 16, v15
	v_and_b32_e32 v20, 0xffff0000, v15
	v_exp_f32_e32 v4, v4
	v_exp_f32_e32 v5, v5
	v_exp_f32_e32 v6, v6
	v_exp_f32_e32 v7, v7
	v_add_f32_e32 v17, v17, v18
	v_add_f32_e32 v18, v19, v20
	v_cvt_pk_bf16_f32 v8, v8, v9
	v_cvt_pk_bf16_f32 v9, v10, v11
	v_add_f32_e32 v17, v17, v18
	v_lshlrev_b32_e32 v10, 16, v8
	v_and_b32_e32 v11, 0xffff0000, v8
	v_lshlrev_b32_e32 v18, 16, v9
	v_and_b32_e32 v19, 0xffff0000, v9
	v_add_f32_e32 v10, v10, v11
	v_add_f32_e32 v11, v18, v19
	v_add_f32_e32 v17, 0, v17
	v_add_f32_e32 v10, v10, v11
	v_cvt_pk_bf16_f32 v4, v4, v5
	v_cvt_pk_bf16_f32 v5, v6, v7
	v_add_f32_e32 v10, v17, v10
	v_lshlrev_b32_e32 v6, 16, v4
	v_and_b32_e32 v7, 0xffff0000, v4
	v_lshlrev_b32_e32 v11, 16, v5
	v_and_b32_e32 v17, 0xffff0000, v5
	v_mul_f32_e32 v2, 0x3fb8aa3b, v2
	v_add_f32_e32 v6, v6, v7
	v_add_f32_e32 v7, v11, v17
	v_mul_f32_e32 v0, 0x3fb8aa3b, v0
	v_mul_f32_e32 v1, 0x3fb8aa3b, v1
	v_exp_f32_e32 v11, v2
	v_mul_f32_e32 v2, 0x3fb8aa3b, v3
	v_exp_f32_e32 v0, v0
	v_exp_f32_e32 v1, v1
	v_exp_f32_e32 v3, v2
	v_add_f32_e32 v2, v6, v7
	v_add_f32_e32 v6, v10, v2
	v_cvt_pk_bf16_f32 v2, v0, v1
	v_cvt_pk_bf16_f32 v3, v11, v3
	v_lshlrev_b32_e32 v0, 16, v2
	v_and_b32_e32 v1, 0xffff0000, v2
	v_lshlrev_b32_e32 v7, 16, v3
	v_and_b32_e32 v10, 0xffff0000, v3
	v_add_f32_e32 v0, v0, v1
	v_add_f32_e32 v1, v7, v10
	v_add_f32_e32 v0, v0, v1
	v_add_f32_e32 v10, v6, v0
	ds_bpermute_b32 v11, v151, v10
	v_lshl_add_u64 v[0:1], s[46:47], 0, v[12:13]
	v_lshl_add_u64 v[0:1], s[74:75], 1, v[0:1]
	v_lshl_add_u64 v[0:1], v[0:1], 0, s[54:55]
	v_lshl_add_u64 v[6:7], v[0:1], 0, v[132:133]
	s_waitcnt lgkmcnt(0)
	v_add_f32_e32 v0, v10, v11
	ds_bpermute_b32 v1, v150, v0
	v_mov_b32_e32 v212, v14
	v_mov_b32_e32 v213, v15
	v_mov_b32_e32 v214, v8
	v_mov_b32_e32 v215, v9
	v_mov_b32_e32 v216, v4
	v_mov_b32_e32 v217, v5
	v_mov_b32_e32 v218, v2
	v_mov_b32_e32 v219, v3
	v_permlane32_swap_b32_e32 v212, v214
	v_permlane32_swap_b32_e32 v213, v215
	v_permlane32_swap_b32_e32 v216, v218
	v_permlane32_swap_b32_e32 v217, v219
	v_permlane16_swap_b32_e32 v212, v214
	v_permlane16_swap_b32_e32 v213, v215
	v_permlane16_swap_b32_e32 v216, v218
	v_permlane16_swap_b32_e32 v217, v219
	v_lshl_add_u64 v[208:209], v[6:7], 0, v[250:251]
	global_store_dwordx4 v[208:209], v[212:215], off
	global_store_dwordx4 v[208:209], v[216:219], off offset:256
	s_and_saveexec_b64 s[28:29], s[6:7]
	s_cbranch_execz .LBB0_381
	s_waitcnt lgkmcnt(0)
	v_add_f32_e32 v2, v0, v1
	v_lshlrev_b32_e32 v0, 2, v16
	v_ashrrev_i32_e32 v1, 31, v0
	v_lshl_add_u64 v[0:1], v[0:1], 2, s[44:45]
	s_ashr_i32 s31, s30, 31
	v_lshl_add_u64 v[0:1], s[30:31], 2, v[0:1]
	global_atomic_add_f32 v[0:1], v2, off
